# stack18 + layer-0 window loop: K fragments loaded straight from global memory in the MFMA operand layout (no LDS image of K)
# baseline (speedup 1.0000x reference)
.LBB0_882:
	v_add_f32_e32 v52, v52, v53
	s_andn2_b64 vcc, exec, s[8:9]
	v_add_f32_e32 v136, v107, v52
	s_cbranch_vccnz .LBB0_846
	s_ashr_i32 s7, s6, 31
	s_ashr_i32 s65, s64, 31
	s_lshl_b64 s[6:7], s[6:7], 1
	s_add_u32 s6, s80, s6
	v_readlane_b32 s10, v254, 40
	s_addc_u32 s7, s81, s7
	s_or_b32 s8, s10, s4
	s_or_b32 s2, s8, s2
	v_add3_u32 v55, v126, s2, 64
	v_mov_b64_e32 v[52:53], s[80:81]
	v_mad_i64_i32 v[52:53], s[8:9], v55, s44, v[52:53]
	v_mov_b32_e32 v51, v1
	v_lshl_add_u64 v[52:53], s[62:63], 1, v[52:53]
	v_lshl_add_u64 v[52:53], v[52:53], 0, v[50:51]
	v_add_co_u32_e32 v56, vcc, s45, v52
	v_sub_u32_e64 v55, v121, 8 clamp
	s_nop 0
	v_addc_co_u32_e32 v57, vcc, 0, v53, vcc
	v_add_co_u32_e32 v58, vcc, s77, v52
	v_min_u32_e32 v55, 48, v55
	s_nop 0
	v_addc_co_u32_e32 v59, vcc, 0, v53, vcc
	v_add_co_u32_e32 v60, vcc, s46, v52
	s_bfe_u32 s2, s68, 0x30003
	s_nop 0
	v_addc_co_u32_e32 v61, vcc, 0, v53, vcc
	v_and_b32_e32 v197, 31, v249
	v_lshrrev_b32_e32 v239, 3, v249
	v_sub_u32_e32 v197, v197, v239
	v_and_b32_e32 v238, 32, v249
	v_lshlrev_b32_e32 v238, 1, v238
	v_and_b32_e32 v239, 7, v249
	v_lshlrev_b32_e32 v239, 4, v239
	v_sub_u32_e32 v238, v238, v239
	v_ashrrev_i32_e32 v239, 31, v238
	v_mad_i64_i32 v[234:235], s[100:101], v197, s44, v[52:53]
	v_lshl_add_u64 v[234:235], v[234:235], 0, v[238:239]
	global_load_dwordx4 v[216:219], v[234:235], off offset:2048
	global_load_dwordx4 v[220:223], v[234:235], off offset:2064
	global_load_dwordx4 v[224:227], v[234:235], off offset:2080
	global_load_dwordx4 v[228:231], v[234:235], off offset:2096
	v_add_u32_e32 v56, s10, v122
	v_sub_u32_e32 v55, v56, v55
	v_add_u32_e32 v56, 1, v55
	v_cmp_gt_u32_e64 s[8:9], 16, v56
	v_add_u32_e32 v56, 2, v55
	v_cmp_gt_u32_e64 s[10:11], 16, v56
	v_add_u32_e32 v56, 3, v55
	v_cmp_gt_u32_e64 s[12:13], 16, v56
	v_add_u32_e32 v56, 8, v55
	v_cmp_gt_u32_e64 s[14:15], 16, v56
	v_add_u32_e32 v56, 9, v55
	v_cmp_gt_u32_e64 s[16:17], 16, v56
	v_add_u32_e32 v56, 10, v55
	v_cmp_gt_u32_e64 s[18:19], 16, v56
	v_add_u32_e32 v56, 11, v55
	v_cmp_gt_u32_e64 s[20:21], 16, v56
	v_add_u32_e32 v56, 17, v55
	v_lshl_add_u64 v[124:125], s[6:7], 0, v[50:51]
	s_lshl_b32 s6, s2, 2
	v_readlane_b32 s7, v254, 19
	v_cmp_gt_u32_e64 s[24:25], 16, v56
	v_add_u32_e32 v56, 18, v55
	s_add_i32 s33, s7, s6
	v_cmp_gt_u32_e64 s[26:27], 16, v56
	v_add_u32_e32 v56, 19, v55
	v_lshl_add_u64 v[52:53], s[80:81], 0, v[50:51]
	v_sub_u32_e64 v50, s33, 4 clamp
	v_cmp_gt_u32_e64 s[28:29], 16, v56
	v_add_u32_e32 v56, 24, v55
	v_min_u32_e32 v50, 24, v50
	s_movk_i32 s6, 0x7c
	s_movk_i32 s22, 0xffef
	v_cmp_gt_u32_e64 s[30:31], 16, v56
	v_add_u32_e32 v56, 25, v55
	v_readlane_b32 s42, v254, 21
	v_mul_lo_u32 v51, v50, s6
	v_cmp_gt_u32_e64 s[6:7], 16, v55
	v_cmp_lt_u32_e64 s[22:23], s22, v55
	v_cmp_gt_u32_e64 s[34:35], 16, v56
	v_add_u32_e32 v56, 26, v55
	v_add_u32_e32 v55, 27, v55
	s_add_i32 s4, s42, s4
	v_cmp_gt_u32_e64 s[38:39], 16, v55
	v_add_u32_e32 v55, s83, v127
	v_add_u32_e32 v131, s4, v126
	v_lshl_add_u64 v[126:127], s[64:65], 1, v[52:53]
	v_lshl_add_u32 v51, v54, 4, v51
	v_lshlrev_b32_e32 v52, 2, v120
	v_sub_u32_e32 v51, v51, v52
	v_mul_u32_u24_e32 v52, 0x7c, v117
	s_mulk_i32 s2, 0x1f0
	v_sub_u32_e32 v51, v51, v52
	v_subrev_u32_e32 v51, s2, v51
	v_readlane_b32 s2, v254, 42
	s_mov_b32 s69, 0
	s_add_i32 s66, s5, -1
	v_add_u32_e32 v132, s2, v51
	v_add_u32_e32 v51, s33, v117
	v_sub_u32_e64 v51, v51, 4 clamp
	v_min_u32_e32 v51, 24, v51
	v_cmp_gt_u32_e64 s[36:37], 16, v56
	s_add_i32 s78, s78, 8
	v_sub_u32_e32 v133, v50, v51
	s_mov_b32 s4, 7
	v_add_u32_e32 v134, v55, v134
	v_add_u32_e32 v197, v197, v131
	v_lshl_add_u64 v[198:199], v[126:127], 0, v[238:239]
	s_add_i32 s98, s4, -5
	s_min_i32 s98, s98, s66
	s_add_i32 s98, s98, s78
	v_lshl_add_u32 v196, s98, 6, v197
	v_mad_i64_i32 v[234:235], s[100:101], v196, s44, v[198:199]
	global_load_dwordx4 v[180:183], v[234:235], off
	global_load_dwordx4 v[184:187], v[234:235], off offset:16
	global_load_dwordx4 v[188:191], v[234:235], off offset:32
	global_load_dwordx4 v[192:195], v[234:235], off offset:48
	s_branch .LBB0_885

.LBB0_885:
	s_waitcnt vmcnt(0)
	ds_read_b32 v236, v1
	ds_read_b32 v236, v1
	ds_read_b32 v236, v1
	ds_read_b32 v236, v1
	ds_read_b32 v236, v1
	ds_read_b32 v236, v1
	ds_read_b32 v236, v1
	ds_read_b32 v236, v1
	s_waitcnt lgkmcnt(3)
	v_mfma_f32_32x32x16_bf16 v[50:65], v[216:219], v[82:85], 0
	s_add_i32 s42, s4, -5
	s_min_i32 s2, s42, s66
	s_add_i32 s2, s2, s78
	v_lshl_add_u32 v138, s2, 6, v131
	s_nop 0
	s_waitcnt lgkmcnt(2)
	v_mfma_f32_32x32x16_bf16 v[50:65], v[220:223], v[86:89], v[50:65]
	s_nop 0
	v_add_u32_e32 v137, s4, v133
	v_add_u32_e32 v114, -7, v137
	v_add_u32_e32 v135, s69, v132
	v_mov_b32_e32 v115, 0xff800000
	s_waitcnt lgkmcnt(1)
	v_mfma_f32_32x32x16_bf16 v[50:65], v[224:227], v[90:93], v[50:65]
	s_nop 0
	s_nop 1
	s_nop 0
	s_nop 0
	s_waitcnt lgkmcnt(0)
	v_mfma_f32_32x32x16_bf16 v[50:65], v[228:231], v[94:97], v[50:65]
	s_nop 0
	s_nop 1
	s_nop 0
	s_nop 0
	s_nop 0
	s_nop 0
	s_nop 0
	s_nop 0
	s_add_i32 s98, s4, -4
	s_min_i32 s98, s98, s66
	s_add_i32 s98, s98, s78
	v_lshl_add_u32 v196, s98, 6, v197
	v_mad_i64_i32 v[234:235], s[100:101], v196, s44, v[198:199]
	global_load_dwordx4 v[216:219], v[234:235], off
	global_load_dwordx4 v[220:223], v[234:235], off offset:16
	global_load_dwordx4 v[224:227], v[234:235], off offset:32
	global_load_dwordx4 v[228:231], v[234:235], off offset:48
	v_cmp_gt_u32_e32 vcc, 8, v114
	ds_read_b32 v200, v135 offset:10400
	ds_read_b32 v201, v135 offset:10404
	ds_read_b32 v202, v135 offset:10408
	ds_read_b32 v203, v135 offset:10412
	ds_read_b32 v204, v135 offset:10432
	ds_read_b32 v205, v135 offset:10436
	ds_read_b32 v206, v135 offset:10440
	ds_read_b32 v207, v135 offset:10444
	ds_read_b32 v208, v135 offset:10464
	ds_read_b32 v209, v135 offset:10468
	ds_read_b32 v210, v135 offset:10472
	ds_read_b32 v211, v135 offset:10476
	ds_read_b32 v212, v135 offset:10496
	ds_read_b32 v213, v135 offset:10500
	ds_read_b32 v214, v135 offset:10504
	ds_read_b32 v215, v135 offset:10508
	s_waitcnt lgkmcnt(12)
	s_and_b64 s[48:49], vcc, s[6:7]
	v_add_f32_e32 v200, v34, v200
	v_cndmask_b32_e64 v115, v252, v200, s[48:49]
	s_and_b64 s[48:49], vcc, s[8:9]
	v_add_f32_e32 v201, v35, v201
	v_cndmask_b32_e64 v114, v252, v201, s[48:49]
	s_and_b64 s[48:49], vcc, s[10:11]
	v_add_f32_e32 v202, v36, v202
	v_cndmask_b32_e64 v35, v252, v202, s[48:49]
	s_and_b64 s[48:49], vcc, s[12:13]
	v_add_f32_e32 v203, v37, v203
	v_cndmask_b32_e64 v34, v252, v203, s[48:49]
	s_waitcnt lgkmcnt(8)
	s_and_b64 s[48:49], vcc, s[14:15]
	v_add_f32_e32 v204, v38, v204
	v_cndmask_b32_e64 v37, v252, v204, s[48:49]
	s_and_b64 s[48:49], vcc, s[16:17]
	v_add_f32_e32 v205, v39, v205
	v_cndmask_b32_e64 v36, v252, v205, s[48:49]
	s_and_b64 s[48:49], vcc, s[18:19]
	v_add_f32_e32 v206, v40, v206
	v_cndmask_b32_e64 v39, v252, v206, s[48:49]
	s_and_b64 s[48:49], vcc, s[20:21]
	v_add_f32_e32 v207, v41, v207
	v_cndmask_b32_e64 v38, v252, v207, s[48:49]
	s_waitcnt lgkmcnt(4)
	s_and_b64 s[48:49], vcc, s[22:23]
	v_add_f32_e32 v208, v42, v208
	v_cndmask_b32_e64 v116, v252, v208, s[48:49]
	s_and_b64 s[48:49], vcc, s[24:25]
	v_add_f32_e32 v209, v43, v209
	v_cndmask_b32_e64 v41, v252, v209, s[48:49]
	s_and_b64 s[48:49], vcc, s[26:27]
	v_add_f32_e32 v210, v44, v210
	v_cndmask_b32_e64 v118, v252, v210, s[48:49]
	s_and_b64 s[48:49], vcc, s[28:29]
	v_add_f32_e32 v211, v45, v211
	v_cndmask_b32_e64 v117, v252, v211, s[48:49]
	s_waitcnt lgkmcnt(0)
	s_and_b64 s[48:49], vcc, s[30:31]
	v_add_f32_e32 v212, v46, v212
	v_cndmask_b32_e64 v120, v252, v212, s[48:49]
	s_and_b64 s[48:49], vcc, s[34:35]
	v_add_f32_e32 v213, v47, v213
	v_cndmask_b32_e64 v119, v252, v213, s[48:49]
	s_and_b64 s[48:49], vcc, s[36:37]
	v_add_f32_e32 v214, v48, v214
	v_cndmask_b32_e64 v139, v252, v214, s[48:49]
	s_and_b64 s[48:49], vcc, s[38:39]
	v_add_f32_e32 v215, v49, v215
	v_cndmask_b32_e64 v121, v252, v215, s[48:49]
	v_max_f32_e32 v40, v114, v114
	v_max_f32_e32 v42, v115, v115
	v_max_f32_e32 v40, v42, v40
	v_max3_f32 v40, v40, v35, v34
	v_max3_f32 v40, v40, v37, v36
	v_max3_f32 v40, v40, v39, v38
	v_max3_f32 v40, v40, v116, v41
	v_max3_f32 v40, v40, v118, v117
	v_max3_f32 v40, v40, v120, v119
	v_max3_f32 v40, v40, v139, v121
	v_mov_b32_e32 v42, v40
	s_nop 1
	v_permlane32_swap_b32_e32 v40, v42
	v_max3_f32 v140, v123, v40, v42
	v_sub_f32_e32 v40, v115, v140
	v_exp_f32_e32 v40, v40
	v_sub_f32_e32 v42, v114, v140
	v_exp_f32_e32 v42, v42
	v_sub_f32_e32 v35, v35, v140
	v_exp_f32_e32 v35, v35
	v_sub_f32_e32 v34, v34, v140
	v_exp_f32_e32 v34, v34
	v_sub_f32_e32 v37, v37, v140
	v_add_f32_e32 v43, 0, v40
	v_exp_f32_e32 v37, v37
	v_sub_f32_e32 v36, v36, v140
	v_add_f32_e32 v43, v42, v43
	v_exp_f32_e32 v36, v36
	v_sub_f32_e32 v39, v39, v140
	v_add_f32_e32 v43, v35, v43
	v_exp_f32_e32 v39, v39
	v_sub_f32_e32 v38, v38, v140
	v_add_f32_e32 v43, v34, v43
	v_exp_f32_e32 v38, v38
	v_add_f32_e32 v43, v37, v43
	v_add_f32_e32 v43, v36, v43
	v_add_f32_e32 v43, v39, v43
	v_add_f32_e32 v46, v38, v43
	v_sub_f32_e32 v43, v116, v140
	v_exp_f32_e32 v43, v43
	v_sub_f32_e32 v41, v41, v140
	v_exp_f32_e32 v41, v41
	v_sub_f32_e32 v44, v118, v140
	v_exp_f32_e32 v44, v44
	v_sub_f32_e32 v45, v117, v140
	v_exp_f32_e32 v45, v45
	v_add_f32_e32 v46, v43, v46
	v_add_f32_e32 v46, v41, v46
	v_add_f32_e32 v46, v44, v46
	v_add_f32_e32 v114, v45, v46
	v_sub_f32_e32 v46, v120, v140
	v_exp_f32_e32 v46, v46
	v_sub_f32_e32 v47, v119, v140
	v_exp_f32_e32 v47, v47
	v_sub_f32_e32 v48, v139, v140
	v_exp_f32_e32 v48, v48
	v_sub_f32_e32 v49, v121, v140
	v_exp_f32_e32 v49, v49
	v_add_f32_e32 v114, v46, v114
	v_add_f32_e32 v114, v47, v114
	v_add_f32_e32 v114, v48, v114
	v_add_f32_e32 v139, v49, v114
	v_mov_b32_e32 v141, v139
	s_nop 1
	v_permlane32_swap_b32_e32 v139, v141
	v_cmp_gt_f32_e32 vcc, v140, v123
	s_cbranch_vccz .LBB0_919
	v_sub_f32_e32 v114, v123, v140
	v_exp_f32_e32 v114, v114
	s_nop 0
	v_mul_f32_e32 v136, v136, v114
	v_pk_mul_f32 v[32:33], v[32:33], v[114:115] op_sel_hi:[1,0]
	v_pk_mul_f32 v[30:31], v[30:31], v[114:115] op_sel_hi:[1,0]
	v_pk_mul_f32 v[28:29], v[28:29], v[114:115] op_sel_hi:[1,0]
	v_pk_mul_f32 v[26:27], v[26:27], v[114:115] op_sel_hi:[1,0]
	v_pk_mul_f32 v[24:25], v[24:25], v[114:115] op_sel_hi:[1,0]
	v_pk_mul_f32 v[22:23], v[22:23], v[114:115] op_sel_hi:[1,0]
	v_pk_mul_f32 v[20:21], v[20:21], v[114:115] op_sel_hi:[1,0]
	v_pk_mul_f32 v[18:19], v[18:19], v[114:115] op_sel_hi:[1,0]
	v_pk_mul_f32 v[16:17], v[16:17], v[114:115] op_sel_hi:[1,0]
	v_pk_mul_f32 v[14:15], v[14:15], v[114:115] op_sel_hi:[1,0]
	v_pk_mul_f32 v[12:13], v[12:13], v[114:115] op_sel_hi:[1,0]
	v_pk_mul_f32 v[10:11], v[10:11], v[114:115] op_sel_hi:[1,0]
	v_pk_mul_f32 v[8:9], v[8:9], v[114:115] op_sel_hi:[1,0]
	v_pk_mul_f32 v[6:7], v[6:7], v[114:115] op_sel_hi:[1,0]
	v_pk_mul_f32 v[4:5], v[4:5], v[114:115] op_sel_hi:[1,0]
	v_pk_mul_f32 v[2:3], v[2:3], v[114:115] op_sel_hi:[1,0]
.LBB0_919:
	v_cvt_pk_bf16_f32 v114, v40, v42
	v_cvt_pk_bf16_f32 v115, v35, v34
	v_cvt_pk_bf16_f32 v116, v37, v36
	v_cvt_pk_bf16_f32 v117, v39, v38
	v_cvt_pk_bf16_f32 v34, v43, v41
	v_cvt_pk_bf16_f32 v35, v44, v45
	v_cvt_pk_bf16_f32 v36, v46, v47
	v_cvt_pk_bf16_f32 v37, v48, v49
	ds_write_b128 v129, v[70:73]
	ds_write_b128 v129, v[66:69] offset:1152
	ds_write_b128 v129, v[74:77] offset:2304
	ds_write_b128 v129, v[78:81] offset:3456
	ds_read_b64_tr_b16 v[38:39], v134
	ds_read_b64_tr_b16 v[40:41], v134 offset:1152
	s_waitcnt lgkmcnt(0)
	v_mfma_f32_32x32x16_bf16 v[18:33], v[38:41], v[114:117], v[18:33]
	s_add_i32 s33, s4, -6
	ds_read_b64_tr_b16 v[42:43], v134 offset:2304
	ds_read_b64_tr_b16 v[44:45], v134 offset:3456
	ds_read_b64_tr_b16 v[48:49], v134 offset:1216
	ds_read_b64_tr_b16 v[46:47], v134 offset:64
	s_min_i32 s2, s33, s66
	s_add_i32 s2, s2, s78
	v_lshl_add_u32 v38, s2, 6, v131
	v_mad_i64_i32 v[74:75], s[48:49], v38, s44, v[124:125]
	s_waitcnt lgkmcnt(2)
	v_mfma_f32_32x32x16_bf16 v[18:33], v[42:45], v[34:37], v[18:33]
	v_add_co_u32_e32 v42, vcc, s46, v74
	ds_read_b64_tr_b16 v[40:41], v134 offset:3520
	ds_read_b64_tr_b16 v[38:39], v134 offset:2368
	v_addc_co_u32_e32 v43, vcc, 0, v75, vcc
	global_load_dwordx4 v[66:69], v[74:75], off
	global_load_dwordx4 v[70:73], v[42:43], off
	v_add_co_u32_e32 v42, vcc, s77, v74
	s_waitcnt lgkmcnt(2)
	v_mfma_f32_32x32x16_bf16 v[2:17], v[46:49], v[114:117], v[2:17]
	v_addc_co_u32_e32 v43, vcc, 0, v75, vcc
	v_add_co_u32_e32 v44, vcc, s45, v74
	s_add_i32 s2, s4, -4
	s_nop 0
	v_addc_co_u32_e32 v45, vcc, 0, v75, vcc
	global_load_dwordx4 v[114:117], v[42:43], off
	global_load_dwordx4 v[118:121], v[44:45], off
	s_nop 0
	ds_read_b32 v236, v1
	s_nop 0
	ds_read_b32 v236, v1
	s_nop 0
	ds_read_b32 v236, v1
	s_nop 0
	ds_read_b32 v236, v1
	s_waitcnt lgkmcnt(4)
	v_mfma_f32_32x32x16_bf16 v[2:17], v[38:41], v[34:37], v[2:17]
	ds_read_b32 v236, v1
	ds_read_b32 v236, v1
	s_min_i32 s43, s2, s66
	s_add_i32 s43, s43, s78
	v_lshl_add_u32 v123, s43, 6, v131
	s_nop 0
	s_nop 0
	s_waitcnt lgkmcnt(1)
	v_mfma_f32_32x32x16_bf16 v[34:49], v[180:183], v[82:85], 0
	s_nop 0
	s_nop 0
	s_cmp_lt_i32 s33, s5
	s_nop 0
	s_nop 0
	s_waitcnt lgkmcnt(0)
	v_mfma_f32_32x32x16_bf16 v[34:49], v[184:187], v[86:89], v[34:49]
	ds_read_b32 v236, v1
	ds_read_b32 v236, v1
	s_waitcnt lgkmcnt(1)
	v_mfma_f32_32x32x16_bf16 v[34:49], v[188:191], v[90:93], v[34:49]
	s_nop 0
	s_nop 0
	s_nop 0
	s_nop 0
	s_nop 1
	s_nop 0
	s_nop 0
	s_nop 0
	s_waitcnt lgkmcnt(0)
	v_mfma_f32_32x32x16_bf16 v[34:49], v[192:195], v[94:97], v[34:49]
	v_mov_b32_e32 v98, 0xff800000
	s_cselect_b64 vcc, -1, 0
	s_add_i32 s98, s4, -3
	s_min_i32 s98, s98, s66
	s_add_i32 s98, s98, s78
	v_lshl_add_u32 v196, s98, 6, v197
	v_mad_i64_i32 v[234:235], s[100:101], v196, s44, v[198:199]
	global_load_dwordx4 v[180:183], v[234:235], off
	global_load_dwordx4 v[184:187], v[234:235], off offset:16
	global_load_dwordx4 v[188:191], v[234:235], off offset:32
	global_load_dwordx4 v[192:195], v[234:235], off offset:48
	v_cndmask_b32_e32 v99, v98, v58, vcc
	v_cndmask_b32_e32 v58, v98, v55, vcc
	v_cndmask_b32_e32 v55, v98, v54, vcc
	v_cndmask_b32_e32 v54, v98, v51, vcc
	v_add_u32_e32 v51, -6, v137
	v_cndmask_b32_e32 v65, v98, v65, vcc
	v_cndmask_b32_e32 v64, v98, v64, vcc
	v_cndmask_b32_e32 v63, v98, v63, vcc
	v_cndmask_b32_e32 v62, v98, v62, vcc
	v_cndmask_b32_e32 v61, v98, v61, vcc
	v_cndmask_b32_e32 v60, v98, v60, vcc
	v_cndmask_b32_e32 v59, v98, v59, vcc
	v_cndmask_b32_e32 v100, v98, v57, vcc
	v_cndmask_b32_e32 v57, v98, v56, vcc
	v_cndmask_b32_e32 v56, v98, v53, vcc
	v_cndmask_b32_e32 v53, v98, v52, vcc
	v_cndmask_b32_e32 v50, v98, v50, vcc
	v_cmp_gt_u32_e32 vcc, 8, v51
	ds_read_b32 v200, v135 offset:10524
	ds_read_b32 v201, v135 offset:10528
	ds_read_b32 v202, v135 offset:10532
	ds_read_b32 v203, v135 offset:10536
	ds_read_b32 v204, v135 offset:10556
	ds_read_b32 v205, v135 offset:10560
	ds_read_b32 v206, v135 offset:10564
	ds_read_b32 v207, v135 offset:10568
	ds_read_b32 v208, v135 offset:10588
	ds_read_b32 v209, v135 offset:10592
	ds_read_b32 v210, v135 offset:10596
	ds_read_b32 v211, v135 offset:10600
	ds_read_b32 v212, v135 offset:10620
	ds_read_b32 v213, v135 offset:10624
	ds_read_b32 v214, v135 offset:10628
	ds_read_b32 v215, v135 offset:10632
	s_waitcnt lgkmcnt(12)
	s_and_b64 s[48:49], vcc, s[6:7]
	v_add_f32_e32 v200, v50, v200
	v_cndmask_b32_e64 v51, v252, v200, s[48:49]
	s_and_b64 s[48:49], vcc, s[8:9]
	v_add_f32_e32 v201, v54, v201
	v_cndmask_b32_e64 v52, v252, v201, s[48:49]
	s_and_b64 s[48:49], vcc, s[10:11]
	v_add_f32_e32 v202, v53, v202
	v_cndmask_b32_e64 v98, v252, v202, s[48:49]
	s_and_b64 s[48:49], vcc, s[12:13]
	v_add_f32_e32 v203, v56, v203
	v_cndmask_b32_e64 v54, v252, v203, s[48:49]
	s_waitcnt lgkmcnt(8)
	s_and_b64 s[48:49], vcc, s[14:15]
	v_add_f32_e32 v204, v55, v204
	v_cndmask_b32_e64 v53, v252, v204, s[48:49]
	s_and_b64 s[48:49], vcc, s[16:17]
	v_add_f32_e32 v205, v58, v205
	v_cndmask_b32_e64 v56, v252, v205, s[48:49]
	s_and_b64 s[48:49], vcc, s[18:19]
	v_add_f32_e32 v206, v57, v206
	v_cndmask_b32_e64 v55, v252, v206, s[48:49]
	s_and_b64 s[48:49], vcc, s[20:21]
	v_add_f32_e32 v207, v100, v207
	v_cndmask_b32_e64 v58, v252, v207, s[48:49]
	s_waitcnt lgkmcnt(4)
	s_and_b64 s[48:49], vcc, s[22:23]
	v_add_f32_e32 v208, v99, v208
	v_cndmask_b32_e64 v57, v252, v208, s[48:49]
	s_and_b64 s[48:49], vcc, s[24:25]
	v_add_f32_e32 v209, v59, v209
	v_cndmask_b32_e64 v100, v252, v209, s[48:49]
	s_and_b64 s[48:49], vcc, s[26:27]
	v_add_f32_e32 v210, v60, v210
	v_cndmask_b32_e64 v99, v252, v210, s[48:49]
	s_and_b64 s[48:49], vcc, s[28:29]
	v_add_f32_e32 v211, v61, v211
	v_cndmask_b32_e64 v102, v252, v211, s[48:49]
	s_waitcnt lgkmcnt(0)
	s_and_b64 s[48:49], vcc, s[30:31]
	v_add_f32_e32 v212, v62, v212
	v_cndmask_b32_e64 v101, v252, v212, s[48:49]
	s_and_b64 s[48:49], vcc, s[34:35]
	v_add_f32_e32 v213, v63, v213
	v_cndmask_b32_e64 v104, v252, v213, s[48:49]
	s_and_b64 s[48:49], vcc, s[36:37]
	v_add_f32_e32 v214, v64, v214
	v_cndmask_b32_e64 v103, v252, v214, s[48:49]
	s_and_b64 s[48:49], vcc, s[38:39]
	v_add_f32_e32 v215, v65, v215
	v_cndmask_b32_e64 v105, v252, v215, s[48:49]
	v_max_f32_e32 v59, v52, v52
	v_max_f32_e32 v60, v51, v51
	v_max_f32_e32 v59, v60, v59
	v_max3_f32 v59, v59, v98, v54
	v_max3_f32 v59, v59, v53, v56
	v_max3_f32 v59, v59, v55, v58
	v_max3_f32 v59, v59, v57, v100
	v_max3_f32 v59, v59, v99, v102
	v_max3_f32 v59, v59, v101, v104
	v_max3_f32 v59, v59, v103, v105
	v_mov_b32_e32 v60, v59
	s_nop 1
	v_permlane32_swap_b32_e32 v59, v60
	v_add_f32_e32 v50, v139, v141
	v_max3_f32 v139, v140, v59, v60
	v_sub_f32_e32 v51, v51, v139
	v_exp_f32_e32 v59, v51
	v_sub_f32_e32 v51, v52, v139
	v_exp_f32_e32 v60, v51
	v_sub_f32_e32 v51, v98, v139
	v_exp_f32_e32 v61, v51
	v_sub_f32_e32 v51, v54, v139
	v_exp_f32_e32 v54, v51
	v_sub_f32_e32 v52, v53, v139
	v_add_f32_e32 v51, 0, v59
	v_exp_f32_e32 v53, v52
	v_sub_f32_e32 v52, v56, v139
	v_add_f32_e32 v51, v60, v51
	v_exp_f32_e32 v56, v52
	v_sub_f32_e32 v52, v55, v139
	v_add_f32_e32 v51, v61, v51
	v_exp_f32_e32 v55, v52
	v_sub_f32_e32 v52, v58, v139
	v_add_f32_e32 v51, v54, v51
	v_exp_f32_e32 v58, v52
	v_sub_f32_e32 v52, v57, v139
	v_add_f32_e32 v51, v53, v51
	v_exp_f32_e32 v57, v52
	v_sub_f32_e32 v52, v100, v139
	v_add_f32_e32 v51, v56, v51
	v_exp_f32_e32 v62, v52
	v_sub_f32_e32 v52, v99, v139
	v_add_f32_e32 v51, v55, v51
	v_exp_f32_e32 v63, v52
	v_sub_f32_e32 v52, v102, v139
	v_add_f32_e32 v51, v58, v51
	v_exp_f32_e32 v64, v52
	v_sub_f32_e32 v52, v101, v139
	v_add_f32_e32 v51, v57, v51
	v_exp_f32_e32 v65, v52
	v_sub_f32_e32 v52, v104, v139
	v_add_f32_e32 v51, v62, v51
	v_exp_f32_e32 v98, v52
	v_sub_f32_e32 v52, v103, v139
	v_add_f32_e32 v51, v63, v51
	v_exp_f32_e32 v99, v52
	v_sub_f32_e32 v52, v105, v139
	v_add_f32_e32 v51, v64, v51
	v_exp_f32_e32 v100, v52
	v_add_f32_e32 v51, v65, v51
	v_add_f32_e32 v51, v98, v51
	v_add_f32_e32 v51, v99, v51
	v_add_f32_e32 v51, v100, v51
	v_mov_b32_e32 v52, v51
	v_add_f32_e32 v50, v50, v136
	s_nop 0
	v_permlane32_swap_b32_e32 v51, v52
	v_cmp_gt_f32_e32 vcc, v139, v140
	s_cbranch_vccz .LBB0_953
	v_sub_f32_e32 v101, v140, v139
	v_exp_f32_e32 v102, v101
	s_nop 0
	v_mul_f32_e32 v50, v50, v102
	v_pk_mul_f32 v[32:33], v[32:33], v[102:103] op_sel_hi:[1,0]
	v_pk_mul_f32 v[30:31], v[30:31], v[102:103] op_sel_hi:[1,0]
	v_pk_mul_f32 v[28:29], v[28:29], v[102:103] op_sel_hi:[1,0]
	v_pk_mul_f32 v[26:27], v[26:27], v[102:103] op_sel_hi:[1,0]
	v_pk_mul_f32 v[24:25], v[24:25], v[102:103] op_sel_hi:[1,0]
	v_pk_mul_f32 v[22:23], v[22:23], v[102:103] op_sel_hi:[1,0]
	v_pk_mul_f32 v[20:21], v[20:21], v[102:103] op_sel_hi:[1,0]
	v_pk_mul_f32 v[18:19], v[18:19], v[102:103] op_sel_hi:[1,0]
	v_pk_mul_f32 v[16:17], v[16:17], v[102:103] op_sel_hi:[1,0]
	v_pk_mul_f32 v[14:15], v[14:15], v[102:103] op_sel_hi:[1,0]
	v_pk_mul_f32 v[12:13], v[12:13], v[102:103] op_sel_hi:[1,0]
	v_pk_mul_f32 v[10:11], v[10:11], v[102:103] op_sel_hi:[1,0]
	v_pk_mul_f32 v[8:9], v[8:9], v[102:103] op_sel_hi:[1,0]
	v_pk_mul_f32 v[6:7], v[6:7], v[102:103] op_sel_hi:[1,0]
	v_pk_mul_f32 v[4:5], v[4:5], v[102:103] op_sel_hi:[1,0]
	v_pk_mul_f32 v[2:3], v[2:3], v[102:103] op_sel_hi:[1,0]
.LBB0_953:
	v_cvt_pk_bf16_f32 v102, v59, v60
	v_cvt_pk_bf16_f32 v103, v61, v54
	v_cvt_pk_bf16_f32 v104, v53, v56
	v_cvt_pk_bf16_f32 v105, v55, v58
	v_cvt_pk_bf16_f32 v54, v57, v62
	v_cvt_pk_bf16_f32 v55, v63, v64
	v_cvt_pk_bf16_f32 v56, v65, v98
	v_cvt_pk_bf16_f32 v57, v99, v100
	s_waitcnt vmcnt(7)
	ds_write_b128 v129, v[66:69]
	s_waitcnt vmcnt(6)
	ds_write_b128 v129, v[70:73] offset:1152
	s_waitcnt vmcnt(5)
	ds_write_b128 v129, v[114:117] offset:2304
	s_waitcnt vmcnt(4)
	ds_write_b128 v129, v[118:121] offset:3456
	ds_read_b64_tr_b16 v[58:59], v134
	ds_read_b64_tr_b16 v[60:61], v134 offset:1152
	s_waitcnt lgkmcnt(0)
	v_mfma_f32_32x32x16_bf16 v[18:33], v[58:61], v[102:105], v[18:33]
	v_mad_i64_i32 v[62:63], s[48:49], v138, s44, 0
	v_lshl_add_u64 v[114:115], v[124:125], 0, v[62:63]
	ds_read_b64_tr_b16 v[62:63], v134 offset:2304
	ds_read_b64_tr_b16 v[64:65], v134 offset:3456
	ds_read_b64_tr_b16 v[100:101], v134 offset:1216
	ds_read_b64_tr_b16 v[98:99], v134 offset:64
	v_add_co_u32_e32 v58, vcc, s46, v114
	v_add_f32_e32 v51, v51, v52
	s_nop 0
	v_addc_co_u32_e32 v59, vcc, 0, v115, vcc
	s_waitcnt lgkmcnt(2)
	v_mfma_f32_32x32x16_bf16 v[18:33], v[62:65], v[54:57], v[18:33]
	v_add_co_u32_e32 v62, vcc, s77, v114
	global_load_dwordx4 v[66:69], v[114:115], off
	global_load_dwordx4 v[70:73], v[58:59], off
	v_addc_co_u32_e32 v63, vcc, 0, v115, vcc
	v_add_co_u32_e32 v64, vcc, s45, v114
	ds_read_b64_tr_b16 v[60:61], v134 offset:3520
	ds_read_b64_tr_b16 v[58:59], v134 offset:2368
	v_addc_co_u32_e32 v65, vcc, 0, v115, vcc
	s_waitcnt lgkmcnt(2)
	v_mfma_f32_32x32x16_bf16 v[2:17], v[98:101], v[102:105], v[2:17]
	global_load_dwordx4 v[98:101], v[62:63], off
	global_load_dwordx4 v[102:105], v[64:65], off
	v_add_f32_e32 v136, v51, v50
	s_cmp_ge_i32 s42, s5
	s_mov_b64 s[64:65], -1
	s_waitcnt lgkmcnt(0)
	v_mfma_f32_32x32x16_bf16 v[2:17], v[58:61], v[54:57], v[2:17]
	s_cbranch_scc1 .LBB0_884
	s_nop 0
	ds_read_b32 v236, v1
	s_nop 0
	ds_read_b32 v236, v1
	s_nop 0
	ds_read_b32 v236, v1
	s_nop 0
	ds_read_b32 v236, v1
	ds_read_b32 v236, v1
	ds_read_b32 v236, v1
	ds_read_b32 v236, v1
	ds_read_b32 v236, v1
	s_waitcnt lgkmcnt(3)
	v_mfma_f32_32x32x16_bf16 v[50:65], v[216:219], v[82:85], 0
	s_add_i32 s43, s4, -3
	s_min_i32 s33, s43, s66
	s_add_i32 s33, s33, s78
	v_lshl_add_u32 v115, s33, 6, v131
	s_nop 0
	s_waitcnt lgkmcnt(2)
	v_mfma_f32_32x32x16_bf16 v[50:65], v[220:223], v[86:89], v[50:65]
	s_nop 0
	v_add_u32_e32 v114, -5, v137
	v_mov_b32_e32 v116, 0xff800000
	s_waitcnt lgkmcnt(1)
	v_mfma_f32_32x32x16_bf16 v[50:65], v[224:227], v[90:93], v[50:65]
	s_nop 0
	s_nop 1
	s_nop 0
	s_nop 0
	s_waitcnt lgkmcnt(0)
	v_mfma_f32_32x32x16_bf16 v[50:65], v[228:231], v[94:97], v[50:65]
	s_nop 0
	s_nop 1
	s_nop 0
	s_nop 0
	s_nop 0
	s_nop 0
	s_nop 0
	s_nop 0
	s_add_i32 s98, s4, -2
	s_min_i32 s98, s98, s66
	s_add_i32 s98, s98, s78
	v_lshl_add_u32 v196, s98, 6, v197
	v_mad_i64_i32 v[234:235], s[100:101], v196, s44, v[198:199]
	global_load_dwordx4 v[216:219], v[234:235], off
	global_load_dwordx4 v[220:223], v[234:235], off offset:16
	global_load_dwordx4 v[224:227], v[234:235], off offset:32
	global_load_dwordx4 v[228:231], v[234:235], off offset:48
	v_cmp_gt_u32_e32 vcc, 8, v114
	ds_read_b32 v200, v135 offset:10648
	ds_read_b32 v201, v135 offset:10652
	ds_read_b32 v202, v135 offset:10656
	ds_read_b32 v203, v135 offset:10660
	ds_read_b32 v204, v135 offset:10680
	ds_read_b32 v205, v135 offset:10684
	ds_read_b32 v206, v135 offset:10688
	ds_read_b32 v207, v135 offset:10692
	ds_read_b32 v208, v135 offset:10712
	ds_read_b32 v209, v135 offset:10716
	ds_read_b32 v210, v135 offset:10720
	ds_read_b32 v211, v135 offset:10724
	ds_read_b32 v212, v135 offset:10744
	ds_read_b32 v213, v135 offset:10748
	ds_read_b32 v214, v135 offset:10752
	ds_read_b32 v215, v135 offset:10756
	s_waitcnt lgkmcnt(12)
	s_and_b64 s[48:49], vcc, s[6:7]
	v_add_f32_e32 v200, v34, v200
	v_cndmask_b32_e64 v116, v252, v200, s[48:49]
	s_and_b64 s[48:49], vcc, s[8:9]
	v_add_f32_e32 v201, v35, v201
	v_cndmask_b32_e64 v114, v252, v201, s[48:49]
	s_and_b64 s[48:49], vcc, s[10:11]
	v_add_f32_e32 v202, v36, v202
	v_cndmask_b32_e64 v35, v252, v202, s[48:49]
	s_and_b64 s[48:49], vcc, s[12:13]
	v_add_f32_e32 v203, v37, v203
	v_cndmask_b32_e64 v34, v252, v203, s[48:49]
	s_waitcnt lgkmcnt(8)
	s_and_b64 s[48:49], vcc, s[14:15]
	v_add_f32_e32 v204, v38, v204
	v_cndmask_b32_e64 v37, v252, v204, s[48:49]
	s_and_b64 s[48:49], vcc, s[16:17]
	v_add_f32_e32 v205, v39, v205
	v_cndmask_b32_e64 v36, v252, v205, s[48:49]
	s_and_b64 s[48:49], vcc, s[18:19]
	v_add_f32_e32 v206, v40, v206
	v_cndmask_b32_e64 v39, v252, v206, s[48:49]
	s_and_b64 s[48:49], vcc, s[20:21]
	v_add_f32_e32 v207, v41, v207
	v_cndmask_b32_e64 v38, v252, v207, s[48:49]
	s_waitcnt lgkmcnt(4)
	s_and_b64 s[48:49], vcc, s[22:23]
	v_add_f32_e32 v208, v42, v208
	v_cndmask_b32_e64 v119, v252, v208, s[48:49]
	s_and_b64 s[48:49], vcc, s[24:25]
	v_add_f32_e32 v209, v43, v209
	v_cndmask_b32_e64 v118, v252, v209, s[48:49]
	s_and_b64 s[48:49], vcc, s[26:27]
	v_add_f32_e32 v210, v44, v210
	v_cndmask_b32_e64 v121, v252, v210, s[48:49]
	s_and_b64 s[48:49], vcc, s[28:29]
	v_add_f32_e32 v211, v45, v211
	v_cndmask_b32_e64 v120, v252, v211, s[48:49]
	s_waitcnt lgkmcnt(0)
	s_and_b64 s[48:49], vcc, s[30:31]
	v_add_f32_e32 v212, v46, v212
	v_cndmask_b32_e64 v140, v252, v212, s[48:49]
	s_and_b64 s[48:49], vcc, s[34:35]
	v_add_f32_e32 v213, v47, v213
	v_cndmask_b32_e64 v138, v252, v213, s[48:49]
	s_and_b64 s[48:49], vcc, s[36:37]
	v_add_f32_e32 v214, v48, v214
	v_cndmask_b32_e64 v142, v252, v214, s[48:49]
	s_and_b64 s[48:49], vcc, s[38:39]
	v_add_f32_e32 v215, v49, v215
	v_cndmask_b32_e64 v141, v252, v215, s[48:49]
	v_max_f32_e32 v40, v114, v114
	v_max_f32_e32 v41, v116, v116
	v_max_f32_e32 v40, v41, v40
	v_max3_f32 v40, v40, v35, v34
	v_max3_f32 v40, v40, v37, v36
	v_max3_f32 v40, v40, v39, v38
	v_max3_f32 v40, v40, v119, v118
	v_max3_f32 v40, v40, v121, v120
	v_max3_f32 v40, v40, v140, v138
	v_max3_f32 v40, v40, v142, v141
	v_mov_b32_e32 v41, v40
	s_nop 1
	v_permlane32_swap_b32_e32 v40, v41
	v_max3_f32 v117, v139, v40, v41
	v_sub_f32_e32 v40, v116, v117
	v_exp_f32_e32 v40, v40
	v_sub_f32_e32 v41, v114, v117
	v_exp_f32_e32 v41, v41
	v_sub_f32_e32 v35, v35, v117
	v_exp_f32_e32 v35, v35
	v_sub_f32_e32 v34, v34, v117
	v_exp_f32_e32 v34, v34
	v_sub_f32_e32 v37, v37, v117
	v_add_f32_e32 v42, 0, v40
	v_exp_f32_e32 v37, v37
	v_sub_f32_e32 v36, v36, v117
	v_add_f32_e32 v42, v41, v42
	v_exp_f32_e32 v36, v36
	v_sub_f32_e32 v39, v39, v117
	v_add_f32_e32 v42, v35, v42
	v_exp_f32_e32 v39, v39
	v_sub_f32_e32 v38, v38, v117
	v_add_f32_e32 v42, v34, v42
	v_exp_f32_e32 v38, v38
	v_add_f32_e32 v42, v37, v42
	v_add_f32_e32 v42, v36, v42
	v_add_f32_e32 v42, v39, v42
	v_add_f32_e32 v46, v38, v42
	v_sub_f32_e32 v42, v119, v117
	v_exp_f32_e32 v42, v42
	v_sub_f32_e32 v43, v118, v117
	v_exp_f32_e32 v43, v43
	v_sub_f32_e32 v44, v121, v117
	v_exp_f32_e32 v44, v44
	v_sub_f32_e32 v45, v120, v117
	v_exp_f32_e32 v45, v45
	v_add_f32_e32 v46, v42, v46
	v_add_f32_e32 v46, v43, v46
	v_add_f32_e32 v46, v44, v46
	v_add_f32_e32 v114, v45, v46
	v_sub_f32_e32 v46, v140, v117
	v_exp_f32_e32 v46, v46
	v_sub_f32_e32 v47, v138, v117
	v_exp_f32_e32 v47, v47
	v_sub_f32_e32 v48, v142, v117
	v_exp_f32_e32 v48, v48
	v_sub_f32_e32 v49, v141, v117
	v_exp_f32_e32 v49, v49
	v_add_f32_e32 v114, v46, v114
	v_add_f32_e32 v114, v47, v114
	v_add_f32_e32 v114, v48, v114
	v_add_f32_e32 v116, v49, v114
	v_mov_b32_e32 v118, v116
	s_nop 1
	v_permlane32_swap_b32_e32 v116, v118
	v_cmp_gt_f32_e32 vcc, v117, v139
	s_cbranch_vccz .LBB0_988
	v_sub_f32_e32 v114, v139, v117
	v_exp_f32_e32 v114, v114
	s_nop 0
	v_mul_f32_e32 v136, v136, v114
	v_pk_mul_f32 v[32:33], v[32:33], v[114:115] op_sel_hi:[1,0]
	v_pk_mul_f32 v[30:31], v[30:31], v[114:115] op_sel_hi:[1,0]
	v_pk_mul_f32 v[28:29], v[28:29], v[114:115] op_sel_hi:[1,0]
	v_pk_mul_f32 v[26:27], v[26:27], v[114:115] op_sel_hi:[1,0]
	v_pk_mul_f32 v[24:25], v[24:25], v[114:115] op_sel_hi:[1,0]
	v_pk_mul_f32 v[22:23], v[22:23], v[114:115] op_sel_hi:[1,0]
	v_pk_mul_f32 v[20:21], v[20:21], v[114:115] op_sel_hi:[1,0]
	v_pk_mul_f32 v[18:19], v[18:19], v[114:115] op_sel_hi:[1,0]
	v_pk_mul_f32 v[16:17], v[16:17], v[114:115] op_sel_hi:[1,0]
	v_pk_mul_f32 v[14:15], v[14:15], v[114:115] op_sel_hi:[1,0]
	v_pk_mul_f32 v[12:13], v[12:13], v[114:115] op_sel_hi:[1,0]
	v_pk_mul_f32 v[10:11], v[10:11], v[114:115] op_sel_hi:[1,0]
	v_pk_mul_f32 v[8:9], v[8:9], v[114:115] op_sel_hi:[1,0]
	v_pk_mul_f32 v[6:7], v[6:7], v[114:115] op_sel_hi:[1,0]
	v_pk_mul_f32 v[4:5], v[4:5], v[114:115] op_sel_hi:[1,0]
	v_pk_mul_f32 v[2:3], v[2:3], v[114:115] op_sel_hi:[1,0]
.LBB0_988:
	v_cvt_pk_bf16_f32 v138, v40, v41
	v_cvt_pk_bf16_f32 v139, v35, v34
	v_cvt_pk_bf16_f32 v140, v37, v36
	v_cvt_pk_bf16_f32 v141, v39, v38
	v_cvt_pk_bf16_f32 v34, v42, v43
	v_cvt_pk_bf16_f32 v35, v44, v45
	v_cvt_pk_bf16_f32 v36, v46, v47
	v_cvt_pk_bf16_f32 v37, v48, v49
	s_waitcnt vmcnt(7)
	ds_write_b128 v129, v[66:69]
	s_waitcnt vmcnt(6)
	ds_write_b128 v129, v[70:73] offset:1152
	s_waitcnt vmcnt(5)
	ds_write_b128 v129, v[98:101] offset:2304
	s_waitcnt vmcnt(4)
	ds_write_b128 v129, v[102:105] offset:3456
	ds_read_b64_tr_b16 v[38:39], v134
	ds_read_b64_tr_b16 v[40:41], v134 offset:1152
	ds_read_b64_tr_b16 v[44:45], v134 offset:1216
	ds_read_b64_tr_b16 v[42:43], v134 offset:64
	s_waitcnt lgkmcnt(2)
	v_mfma_f32_32x32x16_bf16 v[18:33], v[38:41], v[138:141], v[18:33]
	ds_read_b64_tr_b16 v[38:39], v134 offset:2304
	ds_read_b64_tr_b16 v[40:41], v134 offset:3456
	v_mad_i64_i32 v[46:47], s[48:49], v123, s44, 0
	v_lshl_add_u64 v[98:99], v[124:125], 0, v[46:47]
	ds_read_b64_tr_b16 v[48:49], v134 offset:3520
	ds_read_b64_tr_b16 v[46:47], v134 offset:2368
	s_add_i32 s42, s4, -2
	s_min_i32 s33, s42, s66
	s_waitcnt lgkmcnt(2)
	v_mfma_f32_32x32x16_bf16 v[18:33], v[38:41], v[34:37], v[18:33]
	v_add_co_u32_e32 v38, vcc, s46, v98
	s_add_i32 s33, s33, s78
	s_nop 0
	v_addc_co_u32_e32 v39, vcc, 0, v99, vcc
	global_load_dwordx4 v[66:69], v[98:99], off
	global_load_dwordx4 v[70:73], v[38:39], off
	v_add_co_u32_e32 v38, vcc, s77, v98
	v_mfma_f32_32x32x16_bf16 v[2:17], v[42:45], v[138:141], v[2:17]
	s_nop 0
	v_addc_co_u32_e32 v39, vcc, 0, v99, vcc
	v_add_co_u32_e32 v40, vcc, s45, v98
	v_lshl_add_u32 v114, s33, 6, v131
	s_nop 0
	v_addc_co_u32_e32 v41, vcc, 0, v99, vcc
	global_load_dwordx4 v[98:101], v[38:39], off
	global_load_dwordx4 v[102:105], v[40:41], off
	s_nop 0
	ds_read_b32 v236, v1
	s_nop 0
	ds_read_b32 v236, v1
	s_nop 0
	ds_read_b32 v236, v1
	s_nop 0
	ds_read_b32 v236, v1
	s_waitcnt lgkmcnt(4)
	v_mfma_f32_32x32x16_bf16 v[2:17], v[46:49], v[34:37], v[2:17]
	ds_read_b32 v236, v1
	ds_read_b32 v236, v1
	s_nop 0
	s_nop 0
	s_cmp_lt_i32 s2, s5
	s_nop 0
	s_nop 0
	s_waitcnt lgkmcnt(1)
	v_mfma_f32_32x32x16_bf16 v[34:49], v[180:183], v[82:85], 0
	s_nop 0
	v_mov_b32_e32 v119, 0xff800000
	s_nop 0
	s_nop 0
	s_nop 0
	s_waitcnt lgkmcnt(0)
	v_mfma_f32_32x32x16_bf16 v[34:49], v[184:187], v[86:89], v[34:49]
	ds_read_b32 v236, v1
	ds_read_b32 v236, v1
	s_nop 0
	s_cselect_b64 vcc, -1, 0
	s_nop 0
	v_cndmask_b32_e32 v120, v119, v58, vcc
	v_cndmask_b32_e32 v58, v119, v55, vcc
	s_waitcnt lgkmcnt(1)
	v_mfma_f32_32x32x16_bf16 v[34:49], v[188:191], v[90:93], v[34:49]
	s_nop 0
	s_nop 0
	s_nop 0
	s_nop 0
	s_nop 0
	s_nop 0
	s_nop 0
	v_cndmask_b32_e32 v55, v119, v54, vcc
	v_cndmask_b32_e32 v54, v119, v51, vcc
	v_add_u32_e32 v51, -4, v137
	v_cndmask_b32_e32 v65, v119, v65, vcc
	v_cndmask_b32_e32 v64, v119, v64, vcc
	s_waitcnt lgkmcnt(0)
	v_mfma_f32_32x32x16_bf16 v[34:49], v[192:195], v[94:97], v[34:49]
	s_add_i32 s98, s4, -1
	s_min_i32 s98, s98, s66
	s_add_i32 s98, s98, s78
	v_lshl_add_u32 v196, s98, 6, v197
	v_mad_i64_i32 v[234:235], s[100:101], v196, s44, v[198:199]
	global_load_dwordx4 v[180:183], v[234:235], off
	global_load_dwordx4 v[184:187], v[234:235], off offset:16
	global_load_dwordx4 v[188:191], v[234:235], off offset:32
	global_load_dwordx4 v[192:195], v[234:235], off offset:48
	v_cndmask_b32_e32 v63, v119, v63, vcc
	v_cndmask_b32_e32 v62, v119, v62, vcc
	v_cndmask_b32_e32 v61, v119, v61, vcc
	v_cndmask_b32_e32 v60, v119, v60, vcc
	v_cndmask_b32_e32 v59, v119, v59, vcc
	v_cndmask_b32_e32 v121, v119, v57, vcc
	v_cndmask_b32_e32 v57, v119, v56, vcc
	v_cndmask_b32_e32 v56, v119, v53, vcc
	v_cndmask_b32_e32 v53, v119, v52, vcc
	v_cndmask_b32_e32 v50, v119, v50, vcc
	v_cmp_gt_u32_e32 vcc, 8, v51
	ds_read_b32 v200, v135 offset:10772
	ds_read_b32 v201, v135 offset:10776
	ds_read_b32 v202, v135 offset:10780
	ds_read_b32 v203, v135 offset:10784
	ds_read_b32 v204, v135 offset:10804
	ds_read_b32 v205, v135 offset:10808
	ds_read_b32 v206, v135 offset:10812
	ds_read_b32 v207, v135 offset:10816
	ds_read_b32 v208, v135 offset:10836
	ds_read_b32 v209, v135 offset:10840
	ds_read_b32 v210, v135 offset:10844
	ds_read_b32 v211, v135 offset:10848
	ds_read_b32 v212, v135 offset:10868
	ds_read_b32 v213, v135 offset:10872
	ds_read_b32 v214, v135 offset:10876
	ds_read_b32 v215, v135 offset:10880
	s_waitcnt lgkmcnt(12)
	s_and_b64 s[48:49], vcc, s[6:7]
	v_add_f32_e32 v200, v50, v200
	v_cndmask_b32_e64 v51, v252, v200, s[48:49]
	s_and_b64 s[48:49], vcc, s[8:9]
	v_add_f32_e32 v201, v54, v201
	v_cndmask_b32_e64 v52, v252, v201, s[48:49]
	s_and_b64 s[48:49], vcc, s[10:11]
	v_add_f32_e32 v202, v53, v202
	v_cndmask_b32_e64 v119, v252, v202, s[48:49]
	s_and_b64 s[48:49], vcc, s[12:13]
	v_add_f32_e32 v203, v56, v203
	v_cndmask_b32_e64 v54, v252, v203, s[48:49]
	s_waitcnt lgkmcnt(8)
	s_and_b64 s[48:49], vcc, s[14:15]
	v_add_f32_e32 v204, v55, v204
	v_cndmask_b32_e64 v53, v252, v204, s[48:49]
	s_and_b64 s[48:49], vcc, s[16:17]
	v_add_f32_e32 v205, v58, v205
	v_cndmask_b32_e64 v56, v252, v205, s[48:49]
	s_and_b64 s[48:49], vcc, s[18:19]
	v_add_f32_e32 v206, v57, v206
	v_cndmask_b32_e64 v55, v252, v206, s[48:49]
	s_and_b64 s[48:49], vcc, s[20:21]
	v_add_f32_e32 v207, v121, v207
	v_cndmask_b32_e64 v58, v252, v207, s[48:49]
	s_waitcnt lgkmcnt(4)
	s_and_b64 s[48:49], vcc, s[22:23]
	v_add_f32_e32 v208, v120, v208
	v_cndmask_b32_e64 v57, v252, v208, s[48:49]
	s_and_b64 s[48:49], vcc, s[24:25]
	v_add_f32_e32 v209, v59, v209
	v_cndmask_b32_e64 v121, v252, v209, s[48:49]
	s_and_b64 s[48:49], vcc, s[26:27]
	v_add_f32_e32 v210, v60, v210
	v_cndmask_b32_e64 v120, v252, v210, s[48:49]
	s_and_b64 s[48:49], vcc, s[28:29]
	v_add_f32_e32 v211, v61, v211
	v_cndmask_b32_e64 v138, v252, v211, s[48:49]
	s_waitcnt lgkmcnt(0)
	s_and_b64 s[48:49], vcc, s[30:31]
	v_add_f32_e32 v212, v62, v212
	v_cndmask_b32_e64 v123, v252, v212, s[48:49]
	s_and_b64 s[48:49], vcc, s[34:35]
	v_add_f32_e32 v213, v63, v213
	v_cndmask_b32_e64 v140, v252, v213, s[48:49]
	s_and_b64 s[48:49], vcc, s[36:37]
	v_add_f32_e32 v214, v64, v214
	v_cndmask_b32_e64 v139, v252, v214, s[48:49]
	s_and_b64 s[48:49], vcc, s[38:39]
	v_add_f32_e32 v215, v65, v215
	v_cndmask_b32_e64 v141, v252, v215, s[48:49]
	v_max_f32_e32 v59, v52, v52
	v_max_f32_e32 v60, v51, v51
	v_max_f32_e32 v59, v60, v59
	v_max3_f32 v59, v59, v119, v54
	v_max3_f32 v59, v59, v53, v56
	v_max3_f32 v59, v59, v55, v58
	v_max3_f32 v59, v59, v57, v121
	v_max3_f32 v59, v59, v120, v138
	v_max3_f32 v59, v59, v123, v140
	v_max3_f32 v59, v59, v139, v141
	v_mov_b32_e32 v60, v59
	s_nop 1
	v_permlane32_swap_b32_e32 v59, v60
	v_add_f32_e32 v50, v116, v118
	v_max3_f32 v116, v117, v59, v60
	v_sub_f32_e32 v51, v51, v116
	v_exp_f32_e32 v59, v51
	v_sub_f32_e32 v51, v52, v116
	v_exp_f32_e32 v60, v51
	v_sub_f32_e32 v51, v119, v116
	v_exp_f32_e32 v61, v51
	v_sub_f32_e32 v51, v54, v116
	v_exp_f32_e32 v54, v51
	v_sub_f32_e32 v52, v53, v116
	v_add_f32_e32 v51, 0, v59
	v_exp_f32_e32 v53, v52
	v_sub_f32_e32 v52, v56, v116
	v_add_f32_e32 v51, v60, v51
	v_exp_f32_e32 v56, v52
	v_sub_f32_e32 v52, v55, v116
	v_add_f32_e32 v51, v61, v51
	v_exp_f32_e32 v55, v52
	v_sub_f32_e32 v52, v58, v116
	v_add_f32_e32 v51, v54, v51
	v_exp_f32_e32 v58, v52
	v_sub_f32_e32 v52, v57, v116
	v_add_f32_e32 v51, v53, v51
	v_exp_f32_e32 v57, v52
	v_sub_f32_e32 v52, v121, v116
	v_add_f32_e32 v51, v56, v51
	v_exp_f32_e32 v62, v52
	v_sub_f32_e32 v52, v120, v116
	v_add_f32_e32 v51, v55, v51
	v_exp_f32_e32 v63, v52
	v_sub_f32_e32 v52, v138, v116
	v_add_f32_e32 v51, v58, v51
	v_exp_f32_e32 v64, v52
	v_sub_f32_e32 v52, v123, v116
	v_add_f32_e32 v51, v57, v51
	v_exp_f32_e32 v65, v52
	v_sub_f32_e32 v52, v140, v116
	v_add_f32_e32 v51, v62, v51
	v_exp_f32_e32 v118, v52
	v_sub_f32_e32 v52, v139, v116
	v_add_f32_e32 v51, v63, v51
	v_exp_f32_e32 v119, v52
	v_sub_f32_e32 v52, v141, v116
	v_add_f32_e32 v51, v64, v51
	v_exp_f32_e32 v120, v52
	v_add_f32_e32 v51, v65, v51
	v_add_f32_e32 v51, v118, v51
	v_add_f32_e32 v51, v119, v51
	v_add_f32_e32 v51, v120, v51
	v_mov_b32_e32 v52, v51
	v_add_f32_e32 v50, v50, v136
	s_nop 0
	v_permlane32_swap_b32_e32 v51, v52
	v_cmp_gt_f32_e32 vcc, v116, v117
	s_cbranch_vccz .LBB0_1022
	v_sub_f32_e32 v117, v117, v116
	v_exp_f32_e32 v136, v117
	s_nop 0
	v_mul_f32_e32 v50, v50, v136
	v_pk_mul_f32 v[32:33], v[32:33], v[136:137] op_sel_hi:[1,0]
	v_pk_mul_f32 v[30:31], v[30:31], v[136:137] op_sel_hi:[1,0]
	v_pk_mul_f32 v[28:29], v[28:29], v[136:137] op_sel_hi:[1,0]
	v_pk_mul_f32 v[26:27], v[26:27], v[136:137] op_sel_hi:[1,0]
	v_pk_mul_f32 v[24:25], v[24:25], v[136:137] op_sel_hi:[1,0]
	v_pk_mul_f32 v[22:23], v[22:23], v[136:137] op_sel_hi:[1,0]
	v_pk_mul_f32 v[20:21], v[20:21], v[136:137] op_sel_hi:[1,0]
	v_pk_mul_f32 v[18:19], v[18:19], v[136:137] op_sel_hi:[1,0]
	v_pk_mul_f32 v[16:17], v[16:17], v[136:137] op_sel_hi:[1,0]
	v_pk_mul_f32 v[14:15], v[14:15], v[136:137] op_sel_hi:[1,0]
	v_pk_mul_f32 v[12:13], v[12:13], v[136:137] op_sel_hi:[1,0]
	v_pk_mul_f32 v[10:11], v[10:11], v[136:137] op_sel_hi:[1,0]
	v_pk_mul_f32 v[8:9], v[8:9], v[136:137] op_sel_hi:[1,0]
	v_pk_mul_f32 v[6:7], v[6:7], v[136:137] op_sel_hi:[1,0]
	v_pk_mul_f32 v[4:5], v[4:5], v[136:137] op_sel_hi:[1,0]
	v_pk_mul_f32 v[2:3], v[2:3], v[136:137] op_sel_hi:[1,0]
.LBB0_1022:
	v_cvt_pk_bf16_f32 v138, v59, v60
	v_cvt_pk_bf16_f32 v139, v61, v54
	v_cvt_pk_bf16_f32 v140, v53, v56
	v_cvt_pk_bf16_f32 v141, v55, v58
	v_cvt_pk_bf16_f32 v54, v57, v62
	v_cvt_pk_bf16_f32 v55, v63, v64
	v_cvt_pk_bf16_f32 v56, v65, v118
	v_cvt_pk_bf16_f32 v57, v119, v120
	s_waitcnt vmcnt(7)
	ds_write_b128 v129, v[66:69]
	s_waitcnt vmcnt(6)
	ds_write_b128 v129, v[70:73] offset:1152
	s_waitcnt vmcnt(5)
	ds_write_b128 v129, v[98:101] offset:2304
	s_waitcnt vmcnt(4)
	ds_write_b128 v129, v[102:105] offset:3456
	ds_read_b64_tr_b16 v[58:59], v134
	ds_read_b64_tr_b16 v[60:61], v134 offset:1152
	s_waitcnt lgkmcnt(0)
	v_mfma_f32_32x32x16_bf16 v[18:33], v[58:61], v[138:141], v[18:33]
	v_mad_i64_i32 v[62:63], s[48:49], v115, s44, 0
	v_lshl_add_u64 v[102:103], v[124:125], 0, v[62:63]
	ds_read_b64_tr_b16 v[62:63], v134 offset:2304
	ds_read_b64_tr_b16 v[64:65], v134 offset:3456
	ds_read_b64_tr_b16 v[100:101], v134 offset:1216
	ds_read_b64_tr_b16 v[98:99], v134 offset:64
	v_add_co_u32_e32 v58, vcc, s46, v102
	v_add_f32_e32 v51, v51, v52
	s_nop 0
	v_addc_co_u32_e32 v59, vcc, 0, v103, vcc
	s_waitcnt lgkmcnt(2)
	v_mfma_f32_32x32x16_bf16 v[18:33], v[62:65], v[54:57], v[18:33]
	v_add_co_u32_e32 v62, vcc, s77, v102
	global_load_dwordx4 v[66:69], v[102:103], off
	global_load_dwordx4 v[70:73], v[58:59], off
	v_addc_co_u32_e32 v63, vcc, 0, v103, vcc
	v_add_co_u32_e32 v64, vcc, s45, v102
	ds_read_b64_tr_b16 v[60:61], v134 offset:3520
	ds_read_b64_tr_b16 v[58:59], v134 offset:2368
	v_addc_co_u32_e32 v65, vcc, 0, v103, vcc
	s_waitcnt lgkmcnt(2)
	v_mfma_f32_32x32x16_bf16 v[2:17], v[98:101], v[138:141], v[2:17]
	global_load_dwordx4 v[98:101], v[62:63], off
	global_load_dwordx4 v[102:105], v[64:65], off
	v_add_f32_e32 v136, v51, v50
	s_cmp_ge_i32 s43, s5
	s_waitcnt lgkmcnt(0)
	v_mfma_f32_32x32x16_bf16 v[2:17], v[58:61], v[54:57], v[2:17]
	s_cbranch_scc1 .LBB0_884
	s_nop 0
	ds_read_b32 v236, v1
	s_nop 0
	ds_read_b32 v236, v1
	s_nop 0
	ds_read_b32 v236, v1
	s_nop 0
	ds_read_b32 v236, v1
	ds_read_b32 v236, v1
	ds_read_b32 v236, v1
	ds_read_b32 v236, v1
	ds_read_b32 v236, v1
	s_waitcnt lgkmcnt(3)
	v_mfma_f32_32x32x16_bf16 v[50:65], v[216:219], v[82:85], 0
	s_add_i32 s2, s4, -1
	s_min_i32 s33, s2, s66
	s_add_i32 s33, s33, s78
	v_lshl_add_u32 v138, s33, 6, v131
	s_nop 0
	s_waitcnt lgkmcnt(2)
	v_mfma_f32_32x32x16_bf16 v[50:65], v[220:223], v[86:89], v[50:65]
	s_nop 0
	v_add_u32_e32 v115, -3, v137
	v_mov_b32_e32 v117, 0xff800000
	s_waitcnt lgkmcnt(1)
	v_mfma_f32_32x32x16_bf16 v[50:65], v[224:227], v[90:93], v[50:65]
	s_nop 0
	s_nop 1
	s_nop 0
	s_nop 0
	s_waitcnt lgkmcnt(0)
	v_mfma_f32_32x32x16_bf16 v[50:65], v[228:231], v[94:97], v[50:65]
	s_nop 0
	s_nop 1
	s_nop 0
	s_nop 0
	s_nop 0
	s_nop 0
	s_nop 0
	s_nop 0
	s_add_i32 s98, s4, 0
	s_min_i32 s98, s98, s66
	s_add_i32 s98, s98, s78
	v_lshl_add_u32 v196, s98, 6, v197
	v_mad_i64_i32 v[234:235], s[100:101], v196, s44, v[198:199]
	global_load_dwordx4 v[216:219], v[234:235], off
	global_load_dwordx4 v[220:223], v[234:235], off offset:16
	global_load_dwordx4 v[224:227], v[234:235], off offset:32
	global_load_dwordx4 v[228:231], v[234:235], off offset:48
	v_cmp_gt_u32_e32 vcc, 8, v115
	ds_read_b32 v200, v135 offset:10896
	ds_read_b32 v201, v135 offset:10900
	ds_read_b32 v202, v135 offset:10904
	ds_read_b32 v203, v135 offset:10908
	ds_read_b32 v204, v135 offset:10928
	ds_read_b32 v205, v135 offset:10932
	ds_read_b32 v206, v135 offset:10936
	ds_read_b32 v207, v135 offset:10940
	ds_read_b32 v208, v135 offset:10960
	ds_read_b32 v209, v135 offset:10964
	ds_read_b32 v210, v135 offset:10968
	ds_read_b32 v211, v135 offset:10972
	ds_read_b32 v212, v135 offset:10992
	ds_read_b32 v213, v135 offset:10996
	ds_read_b32 v214, v135 offset:11000
	ds_read_b32 v215, v135 offset:11004
	s_waitcnt lgkmcnt(12)
	s_and_b64 s[48:49], vcc, s[6:7]
	v_add_f32_e32 v200, v34, v200
	v_cndmask_b32_e64 v117, v252, v200, s[48:49]
	s_and_b64 s[48:49], vcc, s[8:9]
	v_add_f32_e32 v201, v35, v201
	v_cndmask_b32_e64 v115, v252, v201, s[48:49]
	s_and_b64 s[48:49], vcc, s[10:11]
	v_add_f32_e32 v202, v36, v202
	v_cndmask_b32_e64 v35, v252, v202, s[48:49]
	s_and_b64 s[48:49], vcc, s[12:13]
	v_add_f32_e32 v203, v37, v203
	v_cndmask_b32_e64 v34, v252, v203, s[48:49]
	s_waitcnt lgkmcnt(8)
	s_and_b64 s[48:49], vcc, s[14:15]
	v_add_f32_e32 v204, v38, v204
	v_cndmask_b32_e64 v37, v252, v204, s[48:49]
	s_and_b64 s[48:49], vcc, s[16:17]
	v_add_f32_e32 v205, v39, v205
	v_cndmask_b32_e64 v36, v252, v205, s[48:49]
	s_and_b64 s[48:49], vcc, s[18:19]
	v_add_f32_e32 v206, v40, v206
	v_cndmask_b32_e64 v39, v252, v206, s[48:49]
	s_and_b64 s[48:49], vcc, s[20:21]
	v_add_f32_e32 v207, v41, v207
	v_cndmask_b32_e64 v38, v252, v207, s[48:49]
	s_waitcnt lgkmcnt(4)
	s_and_b64 s[48:49], vcc, s[22:23]
	v_add_f32_e32 v208, v42, v208
	v_cndmask_b32_e64 v119, v252, v208, s[48:49]
	s_and_b64 s[48:49], vcc, s[24:25]
	v_add_f32_e32 v209, v43, v209
	v_cndmask_b32_e64 v118, v252, v209, s[48:49]
	s_and_b64 s[48:49], vcc, s[26:27]
	v_add_f32_e32 v210, v44, v210
	v_cndmask_b32_e64 v121, v252, v210, s[48:49]
	s_and_b64 s[48:49], vcc, s[28:29]
	v_add_f32_e32 v211, v45, v211
	v_cndmask_b32_e64 v120, v252, v211, s[48:49]
	s_waitcnt lgkmcnt(0)
	s_and_b64 s[48:49], vcc, s[30:31]
	v_add_f32_e32 v212, v46, v212
	v_cndmask_b32_e64 v140, v252, v212, s[48:49]
	s_and_b64 s[48:49], vcc, s[34:35]
	v_add_f32_e32 v213, v47, v213
	v_cndmask_b32_e64 v123, v252, v213, s[48:49]
	s_and_b64 s[48:49], vcc, s[36:37]
	v_add_f32_e32 v214, v48, v214
	v_cndmask_b32_e64 v142, v252, v214, s[48:49]
	s_and_b64 s[48:49], vcc, s[38:39]
	v_add_f32_e32 v215, v49, v215
	v_cndmask_b32_e64 v141, v252, v215, s[48:49]
	v_max_f32_e32 v40, v115, v115
	v_max_f32_e32 v41, v117, v117
	v_max_f32_e32 v40, v41, v40
	v_max3_f32 v40, v40, v35, v34
	v_max3_f32 v40, v40, v37, v36
	v_max3_f32 v40, v40, v39, v38
	v_max3_f32 v40, v40, v119, v118
	v_max3_f32 v40, v40, v121, v120
	v_max3_f32 v40, v40, v140, v123
	v_max3_f32 v40, v40, v142, v141
	v_mov_b32_e32 v41, v40
	s_nop 1
	v_permlane32_swap_b32_e32 v40, v41
	v_max3_f32 v139, v116, v40, v41
	v_sub_f32_e32 v40, v117, v139
	v_exp_f32_e32 v40, v40
	v_sub_f32_e32 v41, v115, v139
	v_exp_f32_e32 v41, v41
	v_sub_f32_e32 v35, v35, v139
	v_exp_f32_e32 v35, v35
	v_sub_f32_e32 v34, v34, v139
	v_exp_f32_e32 v34, v34
	v_sub_f32_e32 v37, v37, v139
	v_add_f32_e32 v42, 0, v40
	v_exp_f32_e32 v37, v37
	v_sub_f32_e32 v36, v36, v139
	v_add_f32_e32 v42, v41, v42
	v_exp_f32_e32 v36, v36
	v_sub_f32_e32 v39, v39, v139
	v_add_f32_e32 v42, v35, v42
	v_exp_f32_e32 v39, v39
	v_sub_f32_e32 v38, v38, v139
	v_add_f32_e32 v42, v34, v42
	v_exp_f32_e32 v38, v38
	v_add_f32_e32 v42, v37, v42
	v_add_f32_e32 v42, v36, v42
	v_add_f32_e32 v42, v39, v42
	v_add_f32_e32 v46, v38, v42
	v_sub_f32_e32 v42, v119, v139
	v_exp_f32_e32 v42, v42
	v_sub_f32_e32 v43, v118, v139
	v_exp_f32_e32 v43, v43
	v_sub_f32_e32 v44, v121, v139
	v_exp_f32_e32 v44, v44
	v_sub_f32_e32 v45, v120, v139
	v_exp_f32_e32 v45, v45
	v_add_f32_e32 v46, v42, v46
	v_add_f32_e32 v46, v43, v46
	v_add_f32_e32 v46, v44, v46
	v_add_f32_e32 v115, v45, v46
	v_sub_f32_e32 v46, v140, v139
	v_exp_f32_e32 v46, v46
	v_sub_f32_e32 v47, v123, v139
	v_exp_f32_e32 v47, v47
	v_sub_f32_e32 v48, v142, v139
	v_exp_f32_e32 v48, v48
	v_sub_f32_e32 v49, v141, v139
	v_exp_f32_e32 v49, v49
	v_add_f32_e32 v115, v46, v115
	v_add_f32_e32 v115, v47, v115
	v_add_f32_e32 v115, v48, v115
	v_add_f32_e32 v123, v49, v115
	v_mov_b32_e32 v140, v123
	s_nop 1
	v_permlane32_swap_b32_e32 v123, v140
	v_cmp_gt_f32_e32 vcc, v139, v116
	s_cbranch_vccz .LBB0_1057
	v_sub_f32_e32 v115, v116, v139
	v_exp_f32_e32 v116, v115
	s_nop 0
	v_mul_f32_e32 v136, v136, v116
	v_pk_mul_f32 v[32:33], v[32:33], v[116:117] op_sel_hi:[1,0]
	v_pk_mul_f32 v[30:31], v[30:31], v[116:117] op_sel_hi:[1,0]
	v_pk_mul_f32 v[28:29], v[28:29], v[116:117] op_sel_hi:[1,0]
	v_pk_mul_f32 v[26:27], v[26:27], v[116:117] op_sel_hi:[1,0]
	v_pk_mul_f32 v[24:25], v[24:25], v[116:117] op_sel_hi:[1,0]
	v_pk_mul_f32 v[22:23], v[22:23], v[116:117] op_sel_hi:[1,0]
	v_pk_mul_f32 v[20:21], v[20:21], v[116:117] op_sel_hi:[1,0]
	v_pk_mul_f32 v[18:19], v[18:19], v[116:117] op_sel_hi:[1,0]
	v_pk_mul_f32 v[16:17], v[16:17], v[116:117] op_sel_hi:[1,0]
	v_pk_mul_f32 v[14:15], v[14:15], v[116:117] op_sel_hi:[1,0]
	v_pk_mul_f32 v[12:13], v[12:13], v[116:117] op_sel_hi:[1,0]
	v_pk_mul_f32 v[10:11], v[10:11], v[116:117] op_sel_hi:[1,0]
	v_pk_mul_f32 v[8:9], v[8:9], v[116:117] op_sel_hi:[1,0]
	v_pk_mul_f32 v[6:7], v[6:7], v[116:117] op_sel_hi:[1,0]
	v_pk_mul_f32 v[4:5], v[4:5], v[116:117] op_sel_hi:[1,0]
	v_pk_mul_f32 v[2:3], v[2:3], v[116:117] op_sel_hi:[1,0]
.LBB0_1057:
	v_cvt_pk_bf16_f32 v116, v40, v41
	v_cvt_pk_bf16_f32 v117, v35, v34
	v_cvt_pk_bf16_f32 v118, v37, v36
	v_cvt_pk_bf16_f32 v119, v39, v38
	v_cvt_pk_bf16_f32 v34, v42, v43
	v_cvt_pk_bf16_f32 v35, v44, v45
	v_cvt_pk_bf16_f32 v36, v46, v47
	v_cvt_pk_bf16_f32 v37, v48, v49
	s_waitcnt vmcnt(7)
	ds_write_b128 v129, v[66:69]
	s_waitcnt vmcnt(6)
	ds_write_b128 v129, v[70:73] offset:1152
	s_waitcnt vmcnt(5)
	ds_write_b128 v129, v[98:101] offset:2304
	s_waitcnt vmcnt(4)
	ds_write_b128 v129, v[102:105] offset:3456
	ds_read_b64_tr_b16 v[38:39], v134
	ds_read_b64_tr_b16 v[40:41], v134 offset:1152
	ds_read_b64_tr_b16 v[44:45], v134 offset:1216
	ds_read_b64_tr_b16 v[42:43], v134 offset:64
	s_waitcnt lgkmcnt(2)
	v_mfma_f32_32x32x16_bf16 v[18:33], v[38:41], v[116:119], v[18:33]
	ds_read_b64_tr_b16 v[38:39], v134 offset:2304
	ds_read_b64_tr_b16 v[40:41], v134 offset:3456
	v_mad_i64_i32 v[46:47], s[48:49], v114, s44, 0
	v_lshl_add_u64 v[98:99], v[124:125], 0, v[46:47]
	ds_read_b64_tr_b16 v[48:49], v134 offset:3520
	ds_read_b64_tr_b16 v[46:47], v134 offset:2368
	s_min_i32 s33, s4, s66
	s_add_i32 s33, s33, s78
	s_waitcnt lgkmcnt(2)
	v_mfma_f32_32x32x16_bf16 v[18:33], v[38:41], v[34:37], v[18:33]
	v_add_co_u32_e32 v38, vcc, s46, v98
	s_cmp_lt_i32 s42, s5
	s_nop 0
	v_addc_co_u32_e32 v39, vcc, 0, v99, vcc
	global_load_dwordx4 v[66:69], v[98:99], off
	global_load_dwordx4 v[70:73], v[38:39], off
	v_add_co_u32_e32 v38, vcc, s77, v98
	v_mfma_f32_32x32x16_bf16 v[2:17], v[42:45], v[116:119], v[2:17]
	s_nop 0
	v_addc_co_u32_e32 v39, vcc, 0, v99, vcc
	v_add_co_u32_e32 v40, vcc, s45, v98
	s_nop 1
	v_addc_co_u32_e32 v41, vcc, 0, v99, vcc
	global_load_dwordx4 v[114:117], v[38:39], off
	global_load_dwordx4 v[118:121], v[40:41], off
	s_nop 0
	ds_read_b32 v236, v1
	s_nop 0
	ds_read_b32 v236, v1
	s_nop 0
	ds_read_b32 v236, v1
	s_nop 0
	ds_read_b32 v236, v1
	s_waitcnt lgkmcnt(4)
	v_mfma_f32_32x32x16_bf16 v[2:17], v[46:49], v[34:37], v[2:17]
	ds_read_b32 v236, v1
	ds_read_b32 v236, v1
	s_waitcnt lgkmcnt(1)
	v_mfma_f32_32x32x16_bf16 v[34:49], v[180:183], v[82:85], 0
	s_waitcnt lgkmcnt(0)
	v_mfma_f32_32x32x16_bf16 v[34:49], v[184:187], v[86:89], v[34:49]
	ds_read_b32 v236, v1
	ds_read_b32 v236, v1
	s_waitcnt lgkmcnt(1)
	v_mfma_f32_32x32x16_bf16 v[34:49], v[188:191], v[90:93], v[34:49]
	v_lshl_add_u32 v74, s33, 6, v131
	s_nop 0
	s_nop 0
	s_nop 1
	s_nop 0
	s_nop 0
	s_nop 0
	s_nop 0
	s_waitcnt lgkmcnt(0)
	v_mfma_f32_32x32x16_bf16 v[34:49], v[192:195], v[94:97], v[34:49]
	s_nop 0
	s_nop 0
	s_nop 1
	s_nop 0
	s_nop 0
	s_nop 0
	v_mov_b32_e32 v74, 0xff800000
	s_cselect_b64 vcc, -1, 0
	s_add_i32 s98, s4, 1
	s_min_i32 s98, s98, s66
	s_add_i32 s98, s98, s78
	v_lshl_add_u32 v196, s98, 6, v197
	v_mad_i64_i32 v[234:235], s[100:101], v196, s44, v[198:199]
	global_load_dwordx4 v[180:183], v[234:235], off
	global_load_dwordx4 v[184:187], v[234:235], off offset:16
	global_load_dwordx4 v[188:191], v[234:235], off offset:32
	global_load_dwordx4 v[192:195], v[234:235], off offset:48
	v_cndmask_b32_e32 v75, v74, v58, vcc
	v_cndmask_b32_e32 v58, v74, v55, vcc
	v_cndmask_b32_e32 v55, v74, v54, vcc
	v_cndmask_b32_e32 v54, v74, v51, vcc
	v_add_u32_e32 v51, -2, v137
	v_cndmask_b32_e32 v65, v74, v65, vcc
	v_cndmask_b32_e32 v64, v74, v64, vcc
	v_cndmask_b32_e32 v63, v74, v63, vcc
	v_cndmask_b32_e32 v62, v74, v62, vcc
	v_cndmask_b32_e32 v61, v74, v61, vcc
	v_cndmask_b32_e32 v60, v74, v60, vcc
	v_cndmask_b32_e32 v59, v74, v59, vcc
	v_cndmask_b32_e32 v76, v74, v57, vcc
	v_cndmask_b32_e32 v57, v74, v56, vcc
	v_cndmask_b32_e32 v56, v74, v53, vcc
	v_cndmask_b32_e32 v53, v74, v52, vcc
	v_cndmask_b32_e32 v50, v74, v50, vcc
	v_cmp_gt_u32_e32 vcc, 8, v51
	ds_read_b32 v200, v135 offset:11020
	ds_read_b32 v201, v135 offset:11024
	ds_read_b32 v202, v135 offset:11028
	ds_read_b32 v203, v135 offset:11032
	ds_read_b32 v204, v135 offset:11052
	ds_read_b32 v205, v135 offset:11056
	ds_read_b32 v206, v135 offset:11060
	ds_read_b32 v207, v135 offset:11064
	ds_read_b32 v208, v135 offset:11084
	ds_read_b32 v209, v135 offset:11088
	ds_read_b32 v210, v135 offset:11092
	ds_read_b32 v211, v135 offset:11096
	ds_read_b32 v212, v135 offset:11116
	ds_read_b32 v213, v135 offset:11120
	ds_read_b32 v214, v135 offset:11124
	ds_read_b32 v215, v135 offset:11128
	s_waitcnt lgkmcnt(12)
	s_and_b64 s[42:43], vcc, s[6:7]
	v_add_f32_e32 v200, v50, v200
	v_cndmask_b32_e64 v51, v252, v200, s[42:43]
	s_and_b64 s[42:43], vcc, s[8:9]
	v_add_f32_e32 v201, v54, v201
	v_cndmask_b32_e64 v52, v252, v201, s[42:43]
	s_and_b64 s[42:43], vcc, s[10:11]
	v_add_f32_e32 v202, v53, v202
	v_cndmask_b32_e64 v74, v252, v202, s[42:43]
	s_and_b64 s[42:43], vcc, s[12:13]
	v_add_f32_e32 v203, v56, v203
	v_cndmask_b32_e64 v54, v252, v203, s[42:43]
	s_waitcnt lgkmcnt(8)
	s_and_b64 s[42:43], vcc, s[14:15]
	v_add_f32_e32 v204, v55, v204
	v_cndmask_b32_e64 v53, v252, v204, s[42:43]
	s_and_b64 s[42:43], vcc, s[16:17]
	v_add_f32_e32 v205, v58, v205
	v_cndmask_b32_e64 v56, v252, v205, s[42:43]
	s_and_b64 s[42:43], vcc, s[18:19]
	v_add_f32_e32 v206, v57, v206
	v_cndmask_b32_e64 v55, v252, v206, s[42:43]
	s_and_b64 s[42:43], vcc, s[20:21]
	v_add_f32_e32 v207, v76, v207
	v_cndmask_b32_e64 v58, v252, v207, s[42:43]
	s_waitcnt lgkmcnt(4)
	s_and_b64 s[42:43], vcc, s[22:23]
	v_add_f32_e32 v208, v75, v208
	v_cndmask_b32_e64 v57, v252, v208, s[42:43]
	s_and_b64 s[42:43], vcc, s[24:25]
	v_add_f32_e32 v209, v59, v209
	v_cndmask_b32_e64 v76, v252, v209, s[42:43]
	s_and_b64 s[42:43], vcc, s[26:27]
	v_add_f32_e32 v210, v60, v210
	v_cndmask_b32_e64 v75, v252, v210, s[42:43]
	s_and_b64 s[42:43], vcc, s[28:29]
	v_add_f32_e32 v211, v61, v211
	v_cndmask_b32_e64 v78, v252, v211, s[42:43]
	s_waitcnt lgkmcnt(0)
	s_and_b64 s[42:43], vcc, s[30:31]
	v_add_f32_e32 v212, v62, v212
	v_cndmask_b32_e64 v77, v252, v212, s[42:43]
	s_and_b64 s[42:43], vcc, s[34:35]
	v_add_f32_e32 v213, v63, v213
	v_cndmask_b32_e64 v80, v252, v213, s[42:43]
	s_and_b64 s[42:43], vcc, s[36:37]
	v_add_f32_e32 v214, v64, v214
	v_cndmask_b32_e64 v79, v252, v214, s[42:43]
	s_and_b64 s[42:43], vcc, s[38:39]
	v_add_f32_e32 v215, v65, v215
	v_cndmask_b32_e64 v81, v252, v215, s[42:43]
	v_max_f32_e32 v59, v52, v52
	v_max_f32_e32 v60, v51, v51
	v_max_f32_e32 v59, v60, v59
	v_max3_f32 v59, v59, v74, v54
	v_max3_f32 v59, v59, v53, v56
	v_max3_f32 v59, v59, v55, v58
	v_max3_f32 v59, v59, v57, v76
	v_max3_f32 v59, v59, v75, v78
	v_max3_f32 v59, v59, v77, v80
	v_max3_f32 v59, v59, v79, v81
	v_mov_b32_e32 v60, v59
	s_nop 1
	v_permlane32_swap_b32_e32 v59, v60
	v_add_f32_e32 v50, v123, v140
	v_max3_f32 v123, v139, v59, v60
	v_sub_f32_e32 v51, v51, v123
	v_exp_f32_e32 v59, v51
	v_sub_f32_e32 v51, v52, v123
	v_exp_f32_e32 v60, v51
	v_sub_f32_e32 v51, v74, v123
	v_exp_f32_e32 v61, v51
	v_sub_f32_e32 v51, v54, v123
	v_exp_f32_e32 v54, v51
	v_sub_f32_e32 v52, v53, v123
	v_add_f32_e32 v51, 0, v59
	v_exp_f32_e32 v53, v52
	v_sub_f32_e32 v52, v56, v123
	v_add_f32_e32 v51, v60, v51
	v_exp_f32_e32 v56, v52
	v_sub_f32_e32 v52, v55, v123
	v_add_f32_e32 v51, v61, v51
	v_exp_f32_e32 v55, v52
	v_sub_f32_e32 v52, v58, v123
	v_add_f32_e32 v51, v54, v51
	v_exp_f32_e32 v58, v52
	v_sub_f32_e32 v52, v57, v123
	v_add_f32_e32 v51, v53, v51
	v_exp_f32_e32 v57, v52
	v_sub_f32_e32 v52, v76, v123
	v_add_f32_e32 v51, v56, v51
	v_exp_f32_e32 v62, v52
	v_sub_f32_e32 v52, v75, v123
	v_add_f32_e32 v51, v55, v51
	v_exp_f32_e32 v63, v52
	v_sub_f32_e32 v52, v78, v123
	v_add_f32_e32 v51, v58, v51
	v_exp_f32_e32 v64, v52
	v_sub_f32_e32 v52, v77, v123
	v_add_f32_e32 v51, v57, v51
	v_exp_f32_e32 v65, v52
	v_sub_f32_e32 v52, v80, v123
	v_add_f32_e32 v51, v62, v51
	v_exp_f32_e32 v74, v52
	v_sub_f32_e32 v52, v79, v123
	v_add_f32_e32 v51, v63, v51
	v_exp_f32_e32 v75, v52
	v_sub_f32_e32 v52, v81, v123
	v_add_f32_e32 v51, v64, v51
	v_exp_f32_e32 v76, v52
	v_add_f32_e32 v51, v65, v51
	v_add_f32_e32 v51, v74, v51
	v_add_f32_e32 v51, v75, v51
	v_add_f32_e32 v51, v76, v51
	v_mov_b32_e32 v52, v51
	v_add_f32_e32 v50, v50, v136
	s_nop 0
	v_permlane32_swap_b32_e32 v51, v52
	v_cmp_gt_f32_e32 vcc, v123, v139
	s_cbranch_vccz .LBB0_1091
	v_sub_f32_e32 v77, v139, v123
	v_exp_f32_e32 v78, v77
	s_nop 0
	v_mul_f32_e32 v50, v50, v78
	v_pk_mul_f32 v[32:33], v[32:33], v[78:79] op_sel_hi:[1,0]
	v_pk_mul_f32 v[30:31], v[30:31], v[78:79] op_sel_hi:[1,0]
	v_pk_mul_f32 v[28:29], v[28:29], v[78:79] op_sel_hi:[1,0]
	v_pk_mul_f32 v[26:27], v[26:27], v[78:79] op_sel_hi:[1,0]
	v_pk_mul_f32 v[24:25], v[24:25], v[78:79] op_sel_hi:[1,0]
	v_pk_mul_f32 v[22:23], v[22:23], v[78:79] op_sel_hi:[1,0]
	v_pk_mul_f32 v[20:21], v[20:21], v[78:79] op_sel_hi:[1,0]
	v_pk_mul_f32 v[18:19], v[18:19], v[78:79] op_sel_hi:[1,0]
	v_pk_mul_f32 v[16:17], v[16:17], v[78:79] op_sel_hi:[1,0]
	v_pk_mul_f32 v[14:15], v[14:15], v[78:79] op_sel_hi:[1,0]
	v_pk_mul_f32 v[12:13], v[12:13], v[78:79] op_sel_hi:[1,0]
	v_pk_mul_f32 v[10:11], v[10:11], v[78:79] op_sel_hi:[1,0]
	v_pk_mul_f32 v[8:9], v[8:9], v[78:79] op_sel_hi:[1,0]
	v_pk_mul_f32 v[6:7], v[6:7], v[78:79] op_sel_hi:[1,0]
	v_pk_mul_f32 v[4:5], v[4:5], v[78:79] op_sel_hi:[1,0]
	v_pk_mul_f32 v[2:3], v[2:3], v[78:79] op_sel_hi:[1,0]
